# P1 in-projection epilogue: per-row rstd cached across units and computed one unit ahead (two serialized slots round trips removed from the critical path)
# baseline (speedup 1.0000x reference)
; #define PG8_STAGE(bufoff, gbase, voff) do { _Pragma("unroll") for (int _i = 0; _i < 2; ++_i) \
;         __builtin_amdgcn_global_load_lds((const unsigned*)((const char*)(gbase) + (voff)[_i]), (PG8_LAS unsigned*)(lds + (bufoff) + ldsw + _i * 8192), 16, 0, 0); } while (0)
; #define PG8_WAIT_V(n) asm volatile("s_waitcnt vmcnt(" #n ")" ::: "memory")
; #define PG8_BAR __builtin_amdgcn_s_barrier()
; template <class Epi, class Sched, bool ALIGN_EPI = false, bool SP2 = false>
; __device__ __forceinline__ void gemm_phase(PG8_LAS unsigned char* lds, const Gemm g, const Sched& S, const Epi& E, int wave_in) {
;     ...
;     const int aoff = lds_byte(wr * 64 + fr, fq * 8), boff = lds_byte(wc * 32 + fr, fq * 8);
;     ...
;     Unit cur, nxt; int ui = 0;
;     if (!S.next(0, cur)) return;
;     f32x4 acc[2][2][4][2];
; #pragma unroll
;     for (int a = 0; a < 2; ++a)
; #pragma unroll
;         for (int b = 0; b < 2; ++b)
; #pragma unroll
;             for (int m = 0; m < 4; ++m)
; #pragma unroll
;                 for (int n = 0; n < 2; ++n) acc[a][b][m][n] = (f32x4){0.f, 0.f, 0.f, 0.f};
;     bf16x8 At[4][2], B0[2][2], B1[2][2];
;     const char* cA = (const char*)g.A + (size_t)(cur.pm >> g.ash) * g.astride + (size_t)cur.pm * tstep; const char* cB = (const char*)g.Bt + (size_t)(cur.pm >> g.bsh) * g.bstride + (size_t)cur.pn * tstep;
;     S.a_ready(cur);
;     if constexpr (SP2) {
;         PG8_STAGE(PG8_SB(0, 0), cB, voffB); PG8_STAGE(PG8_SB(0, 1), cB + hstep, voffB); PG8_STAGE(PG8_SA(0, 0), cA, voffA); PG8_STAGE(PG8_SA(0, 1), cA + hstep, voffA);
;         if (wr == 1) PG8_BAR;
;         PG8_WAIT_V(2); PG8_BAR;
;         PG8_STAGE(PG8_SB(1, 0), cB + kstep, voffB); PG8_STAGE(PG8_SA(1, 0), cA + kstep, voffA); PG8_STAGE(PG8_SB(1, 1), cB + hstep + kstep, voffB);
;         PG8_WAIT_V(6); PG8_BAR;
.LBB0_267:
	s_add_u32 s12, s12, 0xf100000
	s_addc_u32 s13, s13, 0
	s_add_u32 s18, s16, 0x5500000
	s_addc_u32 s19, s17, 0
	s_add_u32 s20, s10, 0x25100000
	s_addc_u32 s21, s11, 0
	s_and_b32 s83, s9, 3
	s_add_i32 m0, s67, 0x18000
	v_lshl_add_u64 v[6:7], v[6:7], 0, s[88:89]
	s_lshl_b32 s46, s8, 6
	s_lshl_b32 s10, s8, 13
	s_lshl_b32 s47, s83, 5
	s_lshl_b32 s11, s83, 12
	s_waitcnt vmcnt(2)
	s_barrier
	global_load_lds_dwordx4 v[6:7], off
	v_lshl_add_u64 v[4:5], v[4:5], 0, s[88:89]
	s_add_i32 m0, s67, 0x1a000
	s_add_i32 s72, s67, 0x8000
	s_add_i32 s73, s67, 0xa000
	global_load_lds_dwordx4 v[4:5], off
	v_lshl_add_u64 v[0:1], v[0:1], 0, s[88:89]
	s_mov_b32 m0, s72
	s_add_u32 s8, s0, 0x40080
	global_load_lds_dwordx4 v[0:1], off
	v_lshl_add_u64 v[0:1], v[2:3], 0, s[88:89]
	s_mov_b32 m0, s73
	s_addc_u32 s9, s1, 0
	global_load_lds_dwordx4 v[0:1], off
	s_add_i32 m0, s67, 0x1c000
	v_lshl_add_u64 v[0:1], s[8:9], 0, v[132:133]
	global_load_lds_dwordx4 v[0:1], off
	v_lshl_add_u64 v[0:1], s[8:9], 0, v[128:129]
	s_add_i32 m0, s67, 0x1e000
	v_and_b32_e32 v176, 15, v10
	global_load_lds_dwordx4 v[0:1], off
	v_bfe_u32 v1, v10, 4, 2
	v_or_b32_e32 v2, s46, v176
	v_lshlrev_b32_e32 v0, 3, v1
	v_lshlrev_b32_e32 v3, 4, v1
	v_cmp_eq_u32_e64 s[38:39], 0, v1
	v_or_b32_e32 v1, 16, v2
	s_movk_i32 s2, 0xc00
	v_lshlrev_b32_e32 v4, 2, v10
	v_mad_i64_i32 v[138:139], s[8:9], v1, s2, 0
	v_lshlrev_b32_e32 v1, 14, v8
	v_lshl_or_b32 v3, v176, 6, v3
	v_and_b32_e32 v4, 32, v4
	v_and_b32_e32 v1, 0xffff8000, v1
	v_bitop3_b32 v5, v3, s10, v4 bitop3:0xde
	v_bitop3_b32 v177, v3, s11, v4 bitop3:0xde
	v_and_b32_e32 v178, 63, v10
	v_or_b32_e32 v3, 32, v2
	v_or_b32_e32 v4, 48, v2
	v_add_u32_e32 v6, 0x80, v2
	v_add_u32_e32 v7, 0x90, v2
	v_add_u32_e32 v10, 0xa0, v2
	v_add_u32_e32 v15, 0xb0, v2
	v_mad_i64_i32 v[136:137], s[8:9], v2, s2, 0
	v_lshl_add_u32 v1, v9, 11, v1
	v_and_b32_e32 v2, 1, v8
	v_lshl_or_b32 v1, v2, 6, v1
	v_lshl_add_u32 v152, v11, 1, v1
	v_lshlrev_b32_e32 v1, 14, v13
	v_and_b32_e32 v1, 0xffff8000, v1
	s_waitcnt vmcnt(6)
	v_mad_i64_i32 v[140:141], s[8:9], v3, s2, 0
	v_mad_i64_i32 v[142:143], s[8:9], v4, s2, 0
	v_mad_i64_i32 v[144:145], s[8:9], v6, s2, 0
	v_mad_i64_i32 v[146:147], s[8:9], v7, s2, 0
	v_mad_i64_i32 v[148:149], s[8:9], v10, s2, 0
	v_mad_i64_i32 v[150:151], s[8:9], v15, s2, 0
	v_lshl_add_u32 v1, v12, 11, v1
	v_and_b32_e32 v2, 1, v13
	s_cmpk_lt_u32 s6, 0x100
	v_lshl_or_b32 v1, v2, 6, v1
	v_readlane_b32 s2, v254, 40
	v_readlane_b32 s8, v255, 0
	s_cselect_b64 s[26:27], -1, 0
	s_mov_b32 s74, 0
	v_mov_b32_e32 v153, v193
	v_lshl_add_u32 v154, v14, 1, v1
	v_mov_b32_e32 v155, v193
	v_add_u32_e32 v179, 0x100, v5
	v_lshlrev_b32_e32 v192, 1, v0
	s_mov_b32 s60, s2
	s_mov_b32 s6, s8
	s_barrier
	v_readlane_b32 s9, v255, 1
	s_mov_b32 s101, -1
	s_branch .LBB0_270

; __device__ __forceinline__ float row_rstd(const float* slots, int row) {
;     const f32x4* s = (const f32x4*)(slots + (size_t)row * 16);
;     const f32x4 a = s[0], b = s[1], c = s[2], d = s[3];
;     const f32x4 t = (a + b) + (c + d);
;     const float ss = (t[0] + t[1]) + (t[2] + t[3]);
;     return __builtin_amdgcn_rsqf(ss * (1.0f / 1024.0f) + 1e-6f);
; }
; __device__ __forceinline__ void load_rs(const float* slots, int rowbase, int fr, int fq, float scale, float (&rs)[2][4]) {
;     float loc[2];
; #pragma unroll
;     for (int ai = 0; ai < 2; ++ai) loc[ai] = scale * row_rstd(slots, rowbase + ai * HALF + fq * 16 + fr);
; #pragma unroll
;     for (int ai = 0; ai < 2; ++ai)
; #pragma unroll
;         for (int m = 0; m < 4; ++m) rs[ai][m] = __shfl(loc[ai], m * 16 + fr);
; }
;     __device__ __forceinline__ void operator()(const f32x4 (&acc)[2][2][4][2], const Unit& u, int wr, int wc, int fr, int fq) const {
;     ...
;         if (slots) load_rs(slots, u.pm * BM + wr * 64, fr, fq, scale, rs);
.LBB0_276:
	s_lshl_b32 s8, s6, 8
	s_add_i32 s8, s8, s46
	s_mov_b32 s99, 0
	s_cmp_eq_u32 s101, s6
	s_cbranch_scc1 .Lp1_rsok
	v_or_b32_e32 v230, s8, v178
	v_lshlrev_b32_e32 v230, 6, v230
	v_add_u32_e32 v231, 0x2000, v230
	global_load_dwordx4 v[198:201], v230, s[18:19]
	global_load_dwordx4 v[202:205], v230, s[18:19] offset:16
	global_load_dwordx4 v[206:209], v230, s[18:19] offset:32
	global_load_dwordx4 v[210:213], v230, s[18:19] offset:48
	global_load_dwordx4 v[214:217], v231, s[18:19]
	global_load_dwordx4 v[218:221], v231, s[18:19] offset:16
	global_load_dwordx4 v[222:225], v231, s[18:19] offset:32
	global_load_dwordx4 v[226:229], v231, s[18:19] offset:48
	s_waitcnt vmcnt(0)
	v_and_or_b32 v232, v252, 64, v176
	v_pk_add_f32 v[200:201], v[200:201], v[204:205]
	v_pk_add_f32 v[216:217], v[216:217], v[220:221]
	v_pk_add_f32 v[198:199], v[198:199], v[202:203]
	v_pk_add_f32 v[214:215], v[214:215], v[218:219]
	v_pk_add_f32 v[202:203], v[208:209], v[212:213]
	v_pk_add_f32 v[218:219], v[224:225], v[228:229]
	v_pk_add_f32 v[204:205], v[206:207], v[210:211]
	v_pk_add_f32 v[220:221], v[222:223], v[226:227]
	v_pk_add_f32 v[200:201], v[200:201], v[202:203]
	v_pk_add_f32 v[216:217], v[216:217], v[218:219]
	v_pk_add_f32 v[198:199], v[198:199], v[204:205]
	v_pk_add_f32 v[214:215], v[214:215], v[220:221]
	v_lshlrev_b32_e32 v232, 2, v232
	v_add_f32_e32 v198, v198, v199
	v_add_f32_e32 v214, v214, v215
	v_add_f32_e32 v199, v200, v201
	v_add_f32_e32 v215, v216, v217
	v_add_f32_e32 v198, v198, v199
	v_add_f32_e32 v214, v214, v215
	v_fmamk_f32 v198, v198, 0x3a800000, v244
	v_fmamk_f32 v214, v214, 0x3a800000, v244
	v_rsq_f32_e32 v198, v198
	v_rsq_f32_e32 v214, v214
	ds_bpermute_b32 v194, v232, v198
	ds_bpermute_b32 v195, v232, v198 offset:64
	ds_bpermute_b32 v196, v232, v198 offset:128
	ds_bpermute_b32 v197, v232, v198 offset:192
	ds_bpermute_b32 v240, v232, v214
	ds_bpermute_b32 v241, v232, v214 offset:64
	ds_bpermute_b32 v248, v232, v214 offset:128
	ds_bpermute_b32 v249, v232, v214 offset:192
	s_mov_b32 s101, s6
	s_waitcnt lgkmcnt(0)
.Lp1_rsok:
	v_mov_b32_e32 v170, v194
	v_mov_b32_e32 v168, v195
	v_mov_b32_e32 v166, v196
	v_mov_b32_e32 v164, v197
	v_mov_b32_e32 v162, v240
	v_mov_b32_e32 v160, v241
	v_mov_b32_e32 v158, v248
	v_mov_b32_e32 v156, v249
	s_and_b64 vcc, exec, s[40:41]
	s_cbranch_vccz .Lp1_nopf
	s_cmp_eq_u32 s76, s6
	s_cbranch_scc1 .Lp1_nopf
	s_lshl_b32 s98, s76, 8
	s_add_i32 s98, s98, s46
	s_mov_b32 s99, 1
	v_or_b32_e32 v230, s98, v178
	v_lshlrev_b32_e32 v230, 6, v230
	v_add_u32_e32 v231, 0x2000, v230
	global_load_dwordx4 v[198:201], v230, s[18:19]
	global_load_dwordx4 v[202:205], v230, s[18:19] offset:16
	global_load_dwordx4 v[206:209], v230, s[18:19] offset:32
	global_load_dwordx4 v[210:213], v230, s[18:19] offset:48
	global_load_dwordx4 v[214:217], v231, s[18:19]
	global_load_dwordx4 v[218:221], v231, s[18:19] offset:16
	global_load_dwordx4 v[222:225], v231, s[18:19] offset:32
	global_load_dwordx4 v[226:229], v231, s[18:19] offset:48
; __device__ __forceinline__ f32x2 gelu_pk(f32x2 v) {
;     const f32x2 av = __builtin_elementwise_abs(v), d = av * 0.2316418882f + 1.0f;
;     f32x2 t; t.x = __builtin_amdgcn_rcpf(d.x); t.y = __builtin_amdgcn_rcpf(d.y);
;     f32x2 q = t * 0.5307027145f + (-0.7265760135f); q = q * t + 0.7107068705f; q = q * t + (-0.142248368f); q = q * t + 0.127414796f; q = q * t;
;     const f32x2 s = (v * v) * (-0.72134752044f);
;     f32x2 e; e.x = __builtin_amdgcn_exp2f(s.x); e.y = __builtin_amdgcn_exp2f(s.y);
;     const f32x2 m = v * (q * e), r = v - m;
;     f32x2 o; o.x = v.x < 0.f ? m.x : r.x; o.y = v.y < 0.f ? m.y : r.y; return o;
; }
;     __device__ __forceinline__ void operator()(const f32x4 (&acc)[2][2][4][2], const Unit& u, int wr, int wc, int fr, int fq) const {
;     ...
;                 for (int bj = 0; bj < 2; ++bj) { f32x4 v0 = acc[ai][bj][m][0] * sc, v1 = acc[ai][bj][m][1] * sc;
;                     if (do_gelu) { f32x2 a = gelu_pk((f32x2){v0[0], v0[1]}), b = gelu_pk((f32x2){v0[2], v0[3]}), c = gelu_pk((f32x2){v1[0], v1[1]}), d = gelu_pk((f32x2){v1[2], v1[3]});
;                         v0 = (f32x4){a.x, a.y, b.x, b.y}; v1 = (f32x4){c.x, c.y, d.x, d.y}; }
.Lp1_nopf:
	s_cmp_gt_i32 s60, 1
	s_cselect_b64 s[0:1], -1, 0
	s_cmp_lt_i32 s60, 2
	s_waitcnt lgkmcnt(7)
	v_pk_mul_f32 v[126:127], v[126:127], v[170:171] op_sel_hi:[1,0]
	v_pk_mul_f32 v[124:125], v[124:125], v[170:171] op_sel_hi:[1,0]
	v_pk_mul_f32 v[122:123], v[122:123], v[170:171] op_sel_hi:[1,0]
	v_pk_mul_f32 v[172:173], v[120:121], v[170:171] op_sel_hi:[1,0]
	s_cbranch_scc1 .LBB0_278
	v_and_b32_e32 v121, 0x7fffffff, v125
	v_and_b32_e32 v120, 0x7fffffff, v124
	v_pk_fma_f32 v[120:121], v[120:121], s[28:29], 1.0 op_sel_hi:[1,0,0]
	s_mov_b32 s2, 0xbf3a00e3
	v_rcp_f32_e32 v174, v120
	v_rcp_f32_e32 v175, v121
	v_mov_b64_e32 v[120:121], s[2:3]
	v_pk_mul_f32 v[182:183], v[124:125], v[124:125]
	s_mov_b32 s2, 0xbf38aa3b
	v_pk_fma_f32 v[180:181], v[174:175], s[30:31], v[120:121] op_sel_hi:[1,0,0]
	v_pk_mul_f32 v[182:183], v[182:183], s[2:3] op_sel_hi:[1,0]
	v_pk_fma_f32 v[180:181], v[174:175], v[180:181], s[36:37] op_sel_hi:[1,1,0]
	v_exp_f32_e32 v182, v182
	v_exp_f32_e32 v183, v183
	v_pk_fma_f32 v[180:181], v[174:175], v[180:181], s[80:81] op_sel_hi:[1,1,0]
	v_cmp_gt_f32_e32 vcc, 0, v124
	v_pk_fma_f32 v[180:181], v[174:175], v[180:181], s[64:65] op_sel_hi:[1,1,0]
	s_nop 0
	v_pk_mul_f32 v[174:175], v[174:175], v[180:181]
	v_pk_mul_f32 v[180:181], v[126:127], v[126:127]
	v_pk_mul_f32 v[174:175], v[182:183], v[174:175]
	v_pk_mul_f32 v[180:181], v[180:181], s[2:3] op_sel_hi:[1,0]
	v_pk_mul_f32 v[182:183], v[124:125], v[174:175]
	v_pk_fma_f32 v[174:175], v[124:125], v[174:175], v[124:125] neg_lo:[1,0,0] neg_hi:[1,0,0]
	v_exp_f32_e32 v180, v180
	v_cndmask_b32_e32 v124, v174, v182, vcc
	v_cmp_gt_f32_e32 vcc, 0, v125
	v_and_b32_e32 v174, 0x7fffffff, v126
	v_exp_f32_e32 v181, v181
	v_cndmask_b32_e32 v125, v175, v183, vcc
	v_and_b32_e32 v175, 0x7fffffff, v127
	v_pk_fma_f32 v[174:175], v[174:175], s[28:29], 1.0 op_sel_hi:[1,0,0]
	v_cmp_gt_f32_e32 vcc, 0, v126
	v_rcp_f32_e32 v174, v174
	v_rcp_f32_e32 v175, v175
	s_nop 0
	v_pk_fma_f32 v[182:183], v[174:175], s[30:31], v[120:121] op_sel_hi:[1,0,0]
	s_nop 0
	v_pk_fma_f32 v[182:183], v[174:175], v[182:183], s[36:37] op_sel_hi:[1,1,0]
	s_nop 0
	v_pk_fma_f32 v[182:183], v[174:175], v[182:183], s[80:81] op_sel_hi:[1,1,0]
	s_nop 0
	v_pk_fma_f32 v[182:183], v[174:175], v[182:183], s[64:65] op_sel_hi:[1,1,0]
	s_nop 0
	v_pk_mul_f32 v[174:175], v[174:175], v[182:183]
	v_pk_mul_f32 v[182:183], v[172:173], v[172:173]
	v_pk_mul_f32 v[174:175], v[180:181], v[174:175]
	v_pk_mul_f32 v[182:183], v[182:183], s[2:3] op_sel_hi:[1,0]
	v_pk_mul_f32 v[180:181], v[126:127], v[174:175]
	v_pk_fma_f32 v[174:175], v[126:127], v[174:175], v[126:127] neg_lo:[1,0,0] neg_hi:[1,0,0]
	v_exp_f32_e32 v182, v182
	v_cndmask_b32_e32 v126, v174, v180, vcc
	v_cmp_gt_f32_e32 vcc, 0, v127
	v_and_b32_e32 v174, 0x7fffffff, v172
	v_exp_f32_e32 v183, v183
	v_cndmask_b32_e32 v127, v175, v181, vcc
	v_and_b32_e32 v175, 0x7fffffff, v173
	v_pk_fma_f32 v[174:175], v[174:175], s[28:29], 1.0 op_sel_hi:[1,0,0]
	v_cmp_gt_f32_e32 vcc, 0, v172
	v_rcp_f32_e32 v174, v174
	v_rcp_f32_e32 v175, v175
	s_nop 0
	v_pk_fma_f32 v[180:181], v[174:175], s[30:31], v[120:121] op_sel_hi:[1,0,0]
	s_nop 0
	v_pk_fma_f32 v[180:181], v[174:175], v[180:181], s[36:37] op_sel_hi:[1,1,0]
	s_nop 0
	v_pk_fma_f32 v[180:181], v[174:175], v[180:181], s[80:81] op_sel_hi:[1,1,0]
	s_nop 0
	v_pk_fma_f32 v[180:181], v[174:175], v[180:181], s[64:65] op_sel_hi:[1,1,0]
	s_nop 0
	v_pk_mul_f32 v[174:175], v[174:175], v[180:181]
	v_pk_mul_f32 v[180:181], v[122:123], v[122:123]
	v_pk_mul_f32 v[174:175], v[182:183], v[174:175]
	s_nop 0
	v_pk_mul_f32 v[182:183], v[172:173], v[174:175]
	v_pk_fma_f32 v[174:175], v[172:173], v[174:175], v[172:173] neg_lo:[1,0,0] neg_hi:[1,0,0]
	s_nop 0
	v_cndmask_b32_e32 v172, v174, v182, vcc
	v_cmp_gt_f32_e32 vcc, 0, v173
	v_and_b32_e32 v174, 0x7fffffff, v122
	s_nop 0
	v_cndmask_b32_e32 v173, v175, v183, vcc
	v_and_b32_e32 v175, 0x7fffffff, v123
	v_pk_fma_f32 v[174:175], v[174:175], s[28:29], 1.0 op_sel_hi:[1,0,0]
	v_cmp_gt_f32_e32 vcc, 0, v122
	v_rcp_f32_e32 v174, v174
	v_rcp_f32_e32 v175, v175
	s_nop 0
	v_pk_fma_f32 v[120:121], v[174:175], s[30:31], v[120:121] op_sel_hi:[1,0,0]
	s_nop 0
	v_pk_fma_f32 v[120:121], v[174:175], v[120:121], s[36:37] op_sel_hi:[1,1,0]
	s_nop 0
	v_pk_fma_f32 v[120:121], v[174:175], v[120:121], s[80:81] op_sel_hi:[1,1,0]
	s_nop 0
	v_pk_fma_f32 v[120:121], v[174:175], v[120:121], s[64:65] op_sel_hi:[1,1,0]
	s_nop 0
	v_pk_mul_f32 v[120:121], v[174:175], v[120:121]
	v_pk_mul_f32 v[174:175], v[180:181], s[2:3] op_sel_hi:[1,0]
	s_nop 0
	v_exp_f32_e32 v174, v174
	v_exp_f32_e32 v175, v175
	s_nop 0
	v_pk_mul_f32 v[120:121], v[174:175], v[120:121]
	s_nop 0
	v_pk_mul_f32 v[174:175], v[122:123], v[120:121]
	v_pk_fma_f32 v[120:121], v[122:123], v[120:121], v[122:123] neg_lo:[1,0,0] neg_hi:[1,0,0]
	s_nop 0
	v_cndmask_b32_e32 v122, v120, v174, vcc
	v_cmp_gt_f32_e32 vcc, 0, v123
	s_nop 1
	v_cndmask_b32_e32 v123, v121, v175, vcc

; __device__ __forceinline__ float row_rstd(const float* slots, int row) {
;     const f32x4* s = (const f32x4*)(slots + (size_t)row * 16);
;     const f32x4 a = s[0], b = s[1], c = s[2], d = s[3];
;     const f32x4 t = (a + b) + (c + d);
;     const float ss = (t[0] + t[1]) + (t[2] + t[3]);
;     return __builtin_amdgcn_rsqf(ss * (1.0f / 1024.0f) + 1e-6f);
; }
; __device__ __forceinline__ void load_rs(const float* slots, int rowbase, int fr, int fq, float scale, float (&rs)[2][4]) {
;     float loc[2];
; #pragma unroll
;     for (int ai = 0; ai < 2; ++ai) loc[ai] = scale * row_rstd(slots, rowbase + ai * HALF + fq * 16 + fr);
; #pragma unroll
;     for (int ai = 0; ai < 2; ++ai)
; #pragma unroll
;         for (int m = 0; m < 4; ++m) rs[ai][m] = __shfl(loc[ai], m * 16 + fr);
; }
;     __device__ __forceinline__ void operator()(const f32x4 (&acc)[2][2][4][2], const Unit& u, int wr, int wc, int fr, int fq) const {
;     ...
;                 for (int bj = 0; bj < 2; ++bj) { f32x4 v0 = acc[ai][bj][m][0] * sc, v1 = acc[ai][bj][m][1] * sc;
;                     if (do_gelu) { f32x2 a = gelu_pk((f32x2){v0[0], v0[1]}), b = gelu_pk((f32x2){v0[2], v0[3]}), c = gelu_pk((f32x2){v1[0], v1[1]}), d = gelu_pk((f32x2){v1[2], v1[3]});
;                         v0 = (f32x4){a.x, a.y, b.x, b.y}; v1 = (f32x4){c.x, c.y, d.x, d.y}; }
.LBB0_292:
	s_waitcnt lgkmcnt(0)
	s_cmp_eq_u32 s99, 0
	s_cbranch_scc1 .Lp1_nored
	s_waitcnt vmcnt(2)
	v_and_or_b32 v232, v252, 64, v176
	v_pk_add_f32 v[200:201], v[200:201], v[204:205]
	v_pk_add_f32 v[216:217], v[216:217], v[220:221]
	v_pk_add_f32 v[198:199], v[198:199], v[202:203]
	v_pk_add_f32 v[214:215], v[214:215], v[218:219]
	v_pk_add_f32 v[202:203], v[208:209], v[212:213]
	v_pk_add_f32 v[218:219], v[224:225], v[228:229]
	v_pk_add_f32 v[204:205], v[206:207], v[210:211]
	v_pk_add_f32 v[220:221], v[222:223], v[226:227]
	v_pk_add_f32 v[200:201], v[200:201], v[202:203]
	v_pk_add_f32 v[216:217], v[216:217], v[218:219]
	v_pk_add_f32 v[198:199], v[198:199], v[204:205]
	v_pk_add_f32 v[214:215], v[214:215], v[220:221]
	v_lshlrev_b32_e32 v232, 2, v232
	v_add_f32_e32 v198, v198, v199
	v_add_f32_e32 v214, v214, v215
	v_add_f32_e32 v199, v200, v201
	v_add_f32_e32 v215, v216, v217
	v_add_f32_e32 v198, v198, v199
	v_add_f32_e32 v214, v214, v215
	v_fmamk_f32 v198, v198, 0x3a800000, v244
	v_fmamk_f32 v214, v214, 0x3a800000, v244
	v_rsq_f32_e32 v198, v198
	v_rsq_f32_e32 v214, v214
	ds_bpermute_b32 v194, v232, v198
	ds_bpermute_b32 v195, v232, v198 offset:64
	ds_bpermute_b32 v196, v232, v198 offset:128
	ds_bpermute_b32 v197, v232, v198 offset:192
	ds_bpermute_b32 v240, v232, v214
	ds_bpermute_b32 v241, v232, v214 offset:64
	ds_bpermute_b32 v248, v232, v214 offset:128
	ds_bpermute_b32 v249, v232, v214 offset:192
	s_mov_b32 s101, s76
.Lp1_nored:
	v_pk_mul_f32 v[110:111], v[110:111], v[168:169] op_sel_hi:[1,0]
	v_pk_mul_f32 v[108:109], v[108:109], v[168:169] op_sel_hi:[1,0]
	v_pk_mul_f32 v[114:115], v[106:107], v[168:169] op_sel_hi:[1,0]
	s_and_b64 vcc, exec, s[42:43]
	v_pk_mul_f32 v[116:117], v[104:105], v[168:169] op_sel_hi:[1,0]
	s_cbranch_vccnz .LBB0_294
	v_and_b32_e32 v105, 0x7fffffff, v109
	v_and_b32_e32 v104, 0x7fffffff, v108
	v_pk_fma_f32 v[104:105], v[104:105], s[28:29], 1.0 op_sel_hi:[1,0,0]
	s_mov_b32 s0, 0xbf3a00e3
	v_rcp_f32_e32 v106, v104
	v_rcp_f32_e32 v107, v105
	v_mov_b64_e32 v[104:105], s[0:1]
	v_pk_mul_f32 v[124:125], v[108:109], v[108:109]
	s_mov_b32 s0, 0xbf38aa3b
	v_pk_fma_f32 v[122:123], v[106:107], s[30:31], v[104:105] op_sel_hi:[1,0,0]
	v_pk_mul_f32 v[124:125], v[124:125], s[0:1] op_sel_hi:[1,0]
	v_pk_fma_f32 v[122:123], v[106:107], v[122:123], s[36:37] op_sel_hi:[1,1,0]
	v_exp_f32_e32 v124, v124
	v_exp_f32_e32 v125, v125
	v_pk_fma_f32 v[122:123], v[106:107], v[122:123], s[80:81] op_sel_hi:[1,1,0]
	v_cmp_gt_f32_e32 vcc, 0, v108
	v_pk_fma_f32 v[122:123], v[106:107], v[122:123], s[64:65] op_sel_hi:[1,1,0]
	s_nop 0
	v_pk_mul_f32 v[106:107], v[106:107], v[122:123]
	v_pk_mul_f32 v[122:123], v[110:111], v[110:111]
	v_pk_mul_f32 v[106:107], v[124:125], v[106:107]
	v_pk_mul_f32 v[122:123], v[122:123], s[0:1] op_sel_hi:[1,0]
	v_pk_mul_f32 v[124:125], v[108:109], v[106:107]
	v_pk_fma_f32 v[106:107], v[108:109], v[106:107], v[108:109] neg_lo:[1,0,0] neg_hi:[1,0,0]
	v_exp_f32_e32 v122, v122
	v_cndmask_b32_e32 v108, v106, v124, vcc
	v_cmp_gt_f32_e32 vcc, 0, v109
	v_and_b32_e32 v106, 0x7fffffff, v110
	v_exp_f32_e32 v123, v123
	v_cndmask_b32_e32 v109, v107, v125, vcc
	v_and_b32_e32 v107, 0x7fffffff, v111
	v_pk_fma_f32 v[106:107], v[106:107], s[28:29], 1.0 op_sel_hi:[1,0,0]
	v_cmp_gt_f32_e32 vcc, 0, v110
	v_rcp_f32_e32 v106, v106
	v_rcp_f32_e32 v107, v107
	s_nop 0
	v_pk_fma_f32 v[124:125], v[106:107], s[30:31], v[104:105] op_sel_hi:[1,0,0]
	s_nop 0
	v_pk_fma_f32 v[124:125], v[106:107], v[124:125], s[36:37] op_sel_hi:[1,1,0]
	s_nop 0
	v_pk_fma_f32 v[124:125], v[106:107], v[124:125], s[80:81] op_sel_hi:[1,1,0]
	s_nop 0
	v_pk_fma_f32 v[124:125], v[106:107], v[124:125], s[64:65] op_sel_hi:[1,1,0]
	s_nop 0
	v_pk_mul_f32 v[106:107], v[106:107], v[124:125]
	v_pk_mul_f32 v[124:125], v[116:117], v[116:117]
	v_pk_mul_f32 v[106:107], v[122:123], v[106:107]
	v_pk_mul_f32 v[124:125], v[124:125], s[0:1] op_sel_hi:[1,0]
	v_pk_mul_f32 v[122:123], v[110:111], v[106:107]
	v_pk_fma_f32 v[106:107], v[110:111], v[106:107], v[110:111] neg_lo:[1,0,0] neg_hi:[1,0,0]
	v_exp_f32_e32 v124, v124
	v_cndmask_b32_e32 v110, v106, v122, vcc
	v_cmp_gt_f32_e32 vcc, 0, v111
	v_and_b32_e32 v106, 0x7fffffff, v116
	v_exp_f32_e32 v125, v125
	v_cndmask_b32_e32 v111, v107, v123, vcc
	v_and_b32_e32 v107, 0x7fffffff, v117
	v_pk_fma_f32 v[106:107], v[106:107], s[28:29], 1.0 op_sel_hi:[1,0,0]
	v_cmp_gt_f32_e32 vcc, 0, v116
	v_rcp_f32_e32 v106, v106
	v_rcp_f32_e32 v107, v107
	s_nop 0
	v_pk_fma_f32 v[122:123], v[106:107], s[30:31], v[104:105] op_sel_hi:[1,0,0]
	s_nop 0
	v_pk_fma_f32 v[122:123], v[106:107], v[122:123], s[36:37] op_sel_hi:[1,1,0]
	s_nop 0
	v_pk_fma_f32 v[122:123], v[106:107], v[122:123], s[80:81] op_sel_hi:[1,1,0]
	s_nop 0
	v_pk_fma_f32 v[122:123], v[106:107], v[122:123], s[64:65] op_sel_hi:[1,1,0]
	s_nop 0
	v_pk_mul_f32 v[106:107], v[106:107], v[122:123]
	v_pk_mul_f32 v[122:123], v[114:115], v[114:115]
	v_pk_mul_f32 v[106:107], v[124:125], v[106:107]
	s_nop 0
	v_pk_mul_f32 v[124:125], v[116:117], v[106:107]
	v_pk_fma_f32 v[106:107], v[116:117], v[106:107], v[116:117] neg_lo:[1,0,0] neg_hi:[1,0,0]
	s_nop 0
	v_cndmask_b32_e32 v116, v106, v124, vcc
	v_cmp_gt_f32_e32 vcc, 0, v117
	v_and_b32_e32 v106, 0x7fffffff, v114
	s_nop 0
	v_cndmask_b32_e32 v117, v107, v125, vcc
	v_and_b32_e32 v107, 0x7fffffff, v115
	v_pk_fma_f32 v[106:107], v[106:107], s[28:29], 1.0 op_sel_hi:[1,0,0]
	v_cmp_gt_f32_e32 vcc, 0, v114
	v_rcp_f32_e32 v106, v106
	v_rcp_f32_e32 v107, v107
	s_nop 0
	v_pk_fma_f32 v[104:105], v[106:107], s[30:31], v[104:105] op_sel_hi:[1,0,0]
	s_nop 0
	v_pk_fma_f32 v[104:105], v[106:107], v[104:105], s[36:37] op_sel_hi:[1,1,0]
	s_nop 0
	v_pk_fma_f32 v[104:105], v[106:107], v[104:105], s[80:81] op_sel_hi:[1,1,0]
	s_nop 0
	v_pk_fma_f32 v[104:105], v[106:107], v[104:105], s[64:65] op_sel_hi:[1,1,0]
	s_nop 0
	v_pk_mul_f32 v[104:105], v[106:107], v[104:105]
	v_pk_mul_f32 v[106:107], v[122:123], s[0:1] op_sel_hi:[1,0]
	s_nop 0
	v_exp_f32_e32 v106, v106
	v_exp_f32_e32 v107, v107
	s_nop 0
	v_pk_mul_f32 v[104:105], v[106:107], v[104:105]
	s_nop 0
	v_pk_mul_f32 v[106:107], v[114:115], v[104:105]
	v_pk_fma_f32 v[104:105], v[114:115], v[104:105], v[114:115] neg_lo:[1,0,0] neg_hi:[1,0,0]
	s_nop 0
	v_cndmask_b32_e32 v114, v104, v106, vcc
	v_cmp_gt_f32_e32 vcc, 0, v115
	s_nop 1
	v_cndmask_b32_e32 v115, v105, v107, vcc
